# v12 + smaller per-CU start stagger windows (2-3.2 us) at P1/P7/P9/P10 GEMM entries
# speedup vs baseline: 1.0050x; 1.0033x over previous
.LBB0_80:
	s_load_dwordx2 s[2:3], s[82:83], 0x118
	s_load_dwordx2 s[4:5], s[82:83], 0x90
	s_waitcnt lgkmcnt(0)
	s_cmp_lt_i32 s2, 2
	s_cselect_b64 s[2:3], -1, 0
	s_add_u32 s4, s4, 0x2fe00000
	s_addc_u32 s5, s5, 0
	s_and_b64 s[0:1], s[2:3], s[0:1]
	v_writelane_b32 v245, s4, 17
	s_andn2_b64 vcc, exec, s[0:1]
	s_nop 0
	v_writelane_b32 v245, s5, 18
	s_cbranch_vccnz .LBB0_115
	s_cmpk_gt_i32 s81, 0x10ff
	v_readfirstlane_b32 s5, v0
	s_cbranch_scc1 .LBB0_115
	s_memrealtime s[98:99]
	s_and_b32 s100, s81, 0xff
	s_mulk_i32 s100, 0x140
	s_lshr_b32 s100, s100, 8
	s_waitcnt lgkmcnt(0)
	s_add_u32 s100, s98, s100

.LBB0_617:
	v_readlane_b32 s0, v245, 5
	v_readlane_b32 s1, v245, 6
	s_cmp_lt_i32 s0, 8
	s_cselect_b64 s[0:1], -1, 0
	s_and_b64 s[0:1], s[0:1], s[2:3]
	s_andn2_b64 vcc, exec, s[0:1]
	s_cbranch_vccnz .LBB0_642
	s_cmpk_gt_i32 s81, 0x3ff
	v_readfirstlane_b32 s5, v0
	s_cbranch_scc1 .LBB0_642
	s_memrealtime s[98:99]
	s_and_b32 s100, s81, 0xff
	s_mulk_i32 s100, 0x140
	s_lshr_b32 s100, s100, 8
	s_waitcnt lgkmcnt(0)
	s_add_u32 s100, s98, s100

.LBB0_760:
	v_readlane_b32 s2, v245, 5
	v_readlane_b32 s3, v245, 6
	s_cmp_lt_i32 s2, 10
	s_cselect_b64 s[2:3], -1, 0
	s_and_b64 s[0:1], s[2:3], s[0:1]
	s_andn2_b64 vcc, exec, s[0:1]
	s_cbranch_vccnz .LBB0_777
	s_cmpk_gt_i32 s81, 0x15ff
	v_readfirstlane_b32 s5, v0
	s_cbranch_scc1 .LBB0_777
	s_memrealtime s[98:99]
	s_and_b32 s100, s81, 0xff
	s_mulk_i32 s100, 0xc8
	s_lshr_b32 s100, s100, 8
	s_waitcnt lgkmcnt(0)
	s_add_u32 s100, s98, s100

.LBB0_831:
	v_readlane_b32 s0, v245, 5
	v_readlane_b32 s1, v245, 6
	s_cmp_lt_i32 s0, 11
	s_cselect_b64 s[0:1], -1, 0
	s_and_b64 s[2:3], s[0:1], s[2:3]
	s_andn2_b64 vcc, exec, s[2:3]
	s_cbranch_vccnz .LBB0_860
	s_cmpk_gt_i32 s81, 0x3ff
	v_readfirstlane_b32 s4, v0
	s_cbranch_scc1 .LBB0_860
	s_memrealtime s[98:99]
	s_and_b32 s100, s81, 0xff
	s_mulk_i32 s100, 0x140
	s_lshr_b32 s100, s100, 8
	s_waitcnt lgkmcnt(0)
	s_add_u32 s100, s98, s100
